# scan compute waves at s_setprio 3 during the step loop (loader fills leftover issue slots)
# speedup vs baseline: 1.0260x; 1.0054x over previous
; #define SC_GET(X, t) do { const float* p = rec + (t) * 320; w##X = *(const f32x4*)p; a##X = *(const f32x4*)(p + 4); b##X = *(const f32x4*)(p + 8); k##X = *(const f32x4*)(p + 12); q##X = *(const f32x4*)(p + 16); \
;                 v##X = *(const f32x4*)(VVa + (t) * 64); } while (0)
; DI void scan_phase(unsigned char* lds, const Ctx& a, const Op& d, const int variant) {
;     ...
;                 const float* base = (const float*)(lds + bi * SC_BUF);
;                 const float* rec = base + jg * 20; const float* VVa = base + 10240 + rA * 2;
;                 f32x4 wA, aA, bA, kA, qA, vA, wB, aB, bB, kB, qB, vB;
;     ...
;                 SC_GET(A, 0);
; #pragma unroll 2
;                 for (int t = 0; t < SC_T; t += 2) {
;                     SC_GET(B, t + 1);
;                     SC_STEP(A, t);
;                     if (t + 2 < SC_T) SC_GET(A, t + 2);
;                     SC_STEP(B, t + 1);
;                 }
.LBB0_453:
	s_and_b32 s48, s47, 1
	s_and_saveexec_b64 s[10:11], s[8:9]
	s_xor_b64 s[10:11], exec, s[10:11]
	s_cbranch_execz .LBB0_466
	s_setprio 3
	s_mul_i32 s30, s48, 0xd000
	v_add_u32_e32 v175, s30, v157
	v_add_u32_e32 v123, s30, v158
	v_mbcnt_lo_u32_b32 v176, -1, 0
	v_mbcnt_hi_u32_b32 v176, -1, v176
	v_bfe_u32 v177, v176, 3, 1
	v_bfe_u32 v176, v176, 2, 1
	v_lshlrev_b32_e32 v177, 7, v177
	v_lshl_add_u32 v176, v176, 2, v177
	v_add3_u32 v178, v169, s30, v176
	v_cndmask_b32_e64 v176, 0, 1.0, s[4:5]
	v_mov_b32_e32 v177, v176
	s_mov_b32 s34, 0x11111111
	s_mov_b32 s35, 0x11111111
	ds_read_b128 v[40:43], v175
	ds_read_b128 v[44:47], v175 offset:16
	ds_read_b128 v[48:51], v175 offset:32
	ds_read_b128 v[52:55], v175 offset:48
	ds_read_b128 v[56:59], v175 offset:64
	ds_read_b128 v[60:63], v123 offset:40960
	s_mov_b32 s38, 8
	s_waitcnt lgkmcnt(0)
.Lscan_steps:
	s_waitcnt lgkmcnt(1)
	v_pk_mul_f32 v[106:107], v[64:65], v[44:45] op_sel_hi:[1,0]
	ds_read_b128 v[72:75], v175 offset:1280
	v_pk_mul_f32 v[108:109], v[64:65], v[56:57] op_sel_hi:[1,0]
	ds_read_b128 v[76:79], v175 offset:1296
	v_pk_fma_f32 v[106:107], v[66:67], v[44:45], v[106:107] op_sel:[0,1,0]
	ds_read_b128 v[80:83], v175 offset:1312
	v_pk_fma_f32 v[108:109], v[66:67], v[56:57], v[108:109] op_sel:[0,1,0]
	ds_read_b128 v[84:87], v175 offset:1328
	v_pk_fma_f32 v[106:107], v[68:69], v[46:47], v[106:107] op_sel_hi:[1,0,1]
	ds_read_b128 v[88:91], v175 offset:1344
	v_pk_fma_f32 v[108:109], v[68:69], v[58:59], v[108:109] op_sel_hi:[1,0,1]
	ds_read_b128 v[92:95], v123 offset:41216
	v_pk_fma_f32 v[106:107], v[70:71], v[46:47], v[106:107] op_sel:[0,1,0]
	v_swap_b32 v61, v62
	v_pk_fma_f32 v[108:109], v[70:71], v[58:59], v[108:109] op_sel:[0,1,0]
	v_pk_mul_f32 v[110:111], v[64:65], v[40:41] op_sel_hi:[1,0]
	v_add_f32_dpp v106, v106, v106 quad_perm:[1,0,3,2] row_mask:0xf bank_mask:0xf bound_ctrl:1
	v_add_f32_dpp v107, v107, v107 quad_perm:[1,0,3,2] row_mask:0xf bank_mask:0xf bound_ctrl:1
	v_pk_fma_f32 v[108:109], v[62:63], v[176:177], v[108:109]
	v_pk_mul_f32 v[112:113], v[66:67], v[40:41] op_sel:[0,1]
	v_add_f32_dpp v106, v106, v106 quad_perm:[2,3,0,1] row_mask:0xf bank_mask:0xf bound_ctrl:1
	v_add_f32_dpp v107, v107, v107 quad_perm:[2,3,0,1] row_mask:0xf bank_mask:0xf bound_ctrl:1
	v_add_f32_dpp v148, v108, v108 row_half_mirror row_mask:0xf bank_mask:0xf bound_ctrl:1
	v_add_f32_dpp v148, v109, v109 row_half_mirror row_mask:0xf bank_mask:0xa
	v_add_f32_dpp v106, v106, v106 row_half_mirror row_mask:0xf bank_mask:0xf bound_ctrl:1
	v_add_f32_dpp v107, v107, v107 row_half_mirror row_mask:0xf bank_mask:0xf bound_ctrl:1
	v_pk_mul_f32 v[144:145], v[68:69], v[42:43] op_sel_hi:[1,0]
	v_pk_mul_f32 v[146:147], v[70:71], v[42:43] op_sel:[0,1]
	v_add_f32_dpp v106, v106, v106 row_mirror row_mask:0xf bank_mask:0xf bound_ctrl:1
	v_add_f32_dpp v107, v107, v107 row_mirror row_mask:0xf bank_mask:0xf bound_ctrl:1
	v_pk_fma_f32 v[110:111], v[60:61], v[52:53], v[110:111] op_sel_hi:[1,0,1]
	v_pk_fma_f32 v[112:113], v[60:61], v[52:53], v[112:113] op_sel:[0,1,0]
	v_pk_fma_f32 v[144:145], v[60:61], v[54:55], v[144:145] op_sel_hi:[1,0,1]
	v_pk_fma_f32 v[146:147], v[60:61], v[54:55], v[146:147] op_sel:[0,1,0]
	v_pk_fma_f32 v[64:65], v[106:107], v[48:49], v[110:111] op_sel_hi:[1,0,1]
	v_pk_fma_f32 v[66:67], v[106:107], v[48:49], v[112:113] op_sel:[0,1,0]
	v_pk_fma_f32 v[68:69], v[106:107], v[50:51], v[144:145] op_sel_hi:[1,0,1]
	v_pk_fma_f32 v[70:71], v[106:107], v[50:51], v[146:147] op_sel:[0,1,0]
	s_waitcnt lgkmcnt(0)
	v_pk_mul_f32 v[106:107], v[64:65], v[76:77] op_sel_hi:[1,0]
	ds_read_b128 v[40:43], v175 offset:2560
	v_pk_mul_f32 v[108:109], v[64:65], v[88:89] op_sel_hi:[1,0]
	ds_read_b128 v[44:47], v175 offset:2576
	v_pk_fma_f32 v[106:107], v[66:67], v[76:77], v[106:107] op_sel:[0,1,0]
	ds_read_b128 v[48:51], v175 offset:2592
	v_pk_fma_f32 v[108:109], v[66:67], v[88:89], v[108:109] op_sel:[0,1,0]
	ds_read_b128 v[52:55], v175 offset:2608
	v_pk_fma_f32 v[106:107], v[68:69], v[78:79], v[106:107] op_sel_hi:[1,0,1]
	ds_read_b128 v[56:59], v175 offset:2624
	v_pk_fma_f32 v[108:109], v[68:69], v[90:91], v[108:109] op_sel_hi:[1,0,1]
	ds_read_b128 v[60:63], v123 offset:41472
	v_pk_fma_f32 v[106:107], v[70:71], v[78:79], v[106:107] op_sel:[0,1,0]
	v_swap_b32 v93, v94
	v_pk_fma_f32 v[108:109], v[70:71], v[90:91], v[108:109] op_sel:[0,1,0]
	v_pk_mul_f32 v[110:111], v[64:65], v[72:73] op_sel_hi:[1,0]
	v_add_f32_dpp v106, v106, v106 quad_perm:[1,0,3,2] row_mask:0xf bank_mask:0xf bound_ctrl:1
	v_add_f32_dpp v107, v107, v107 quad_perm:[1,0,3,2] row_mask:0xf bank_mask:0xf bound_ctrl:1
	v_pk_fma_f32 v[108:109], v[94:95], v[176:177], v[108:109]
	v_pk_mul_f32 v[112:113], v[66:67], v[72:73] op_sel:[0,1]
	v_add_f32_dpp v106, v106, v106 quad_perm:[2,3,0,1] row_mask:0xf bank_mask:0xf bound_ctrl:1
	v_add_f32_dpp v107, v107, v107 quad_perm:[2,3,0,1] row_mask:0xf bank_mask:0xf bound_ctrl:1
	v_add_f32_dpp v149, v108, v108 row_half_mirror row_mask:0xf bank_mask:0xf bound_ctrl:1
	v_add_f32_dpp v149, v109, v109 row_half_mirror row_mask:0xf bank_mask:0xa
	v_add_f32_dpp v106, v106, v106 row_half_mirror row_mask:0xf bank_mask:0xf bound_ctrl:1
	v_add_f32_dpp v107, v107, v107 row_half_mirror row_mask:0xf bank_mask:0xf bound_ctrl:1
	v_pk_mul_f32 v[144:145], v[68:69], v[74:75] op_sel_hi:[1,0]
	v_pk_mul_f32 v[146:147], v[70:71], v[74:75] op_sel:[0,1]
	v_add_f32_dpp v150, v148, v148 row_ror:8 row_mask:0xf bank_mask:0xf bound_ctrl:1
	v_add_f32_dpp v150, v149, v149 row_ror:8 row_mask:0xf bank_mask:0xc
	v_add_f32_dpp v106, v106, v106 row_mirror row_mask:0xf bank_mask:0xf bound_ctrl:1
	v_add_f32_dpp v107, v107, v107 row_mirror row_mask:0xf bank_mask:0xf bound_ctrl:1
	v_pk_fma_f32 v[110:111], v[92:93], v[84:85], v[110:111] op_sel_hi:[1,0,1]
	v_pk_fma_f32 v[112:113], v[92:93], v[84:85], v[112:113] op_sel:[0,1,0]
	v_pk_fma_f32 v[144:145], v[92:93], v[86:87], v[144:145] op_sel_hi:[1,0,1]
	v_pk_fma_f32 v[146:147], v[92:93], v[86:87], v[146:147] op_sel:[0,1,0]
	v_add_f32_dpp v150, v150, v150 quad_perm:[1,0,3,2] row_mask:0xf bank_mask:0xf bound_ctrl:1
	v_pk_fma_f32 v[64:65], v[106:107], v[80:81], v[110:111] op_sel_hi:[1,0,1]
	v_pk_fma_f32 v[66:67], v[106:107], v[80:81], v[112:113] op_sel:[0,1,0]
	v_add_f32_dpp v150, v150, v150 quad_perm:[2,3,0,1] row_mask:0xf bank_mask:0xf bound_ctrl:1
	v_pk_fma_f32 v[68:69], v[106:107], v[82:83], v[144:145] op_sel_hi:[1,0,1]
	v_pk_fma_f32 v[70:71], v[106:107], v[82:83], v[146:147] op_sel:[0,1,0]
	s_mov_b64 exec, s[34:35]
	ds_write_b32 v178, v150 offset:0
	s_mov_b64 exec, -1
	s_waitcnt lgkmcnt(1)
; #define SC_GET(X, t) do { const float* p = rec + (t) * 320; w##X = *(const f32x4*)p; a##X = *(const f32x4*)(p + 4); b##X = *(const f32x4*)(p + 8); k##X = *(const f32x4*)(p + 12); q##X = *(const f32x4*)(p + 16); \
;                 v##X = *(const f32x4*)(VVa + (t) * 64); } while (0)
; DI void scan_phase(unsigned char* lds, const Ctx& a, const Op& d, const int variant) {
;     ...
;                 SC_GET(A, 0);
; #pragma unroll 2
;                 for (int t = 0; t < SC_T; t += 2) {
;                     SC_GET(B, t + 1);
;                     SC_STEP(A, t);
;                     if (t + 2 < SC_T) SC_GET(A, t + 2);
;                     SC_STEP(B, t + 1);
;                 }
	v_pk_mul_f32 v[106:107], v[64:65], v[44:45] op_sel_hi:[1,0]
	ds_read_b128 v[72:75], v175 offset:3840
	v_pk_mul_f32 v[108:109], v[64:65], v[56:57] op_sel_hi:[1,0]
	ds_read_b128 v[76:79], v175 offset:3856
	v_pk_fma_f32 v[106:107], v[66:67], v[44:45], v[106:107] op_sel:[0,1,0]
	ds_read_b128 v[80:83], v175 offset:3872
	v_pk_fma_f32 v[108:109], v[66:67], v[56:57], v[108:109] op_sel:[0,1,0]
	ds_read_b128 v[84:87], v175 offset:3888
	v_pk_fma_f32 v[106:107], v[68:69], v[46:47], v[106:107] op_sel_hi:[1,0,1]
	ds_read_b128 v[88:91], v175 offset:3904
	v_pk_fma_f32 v[108:109], v[68:69], v[58:59], v[108:109] op_sel_hi:[1,0,1]
	ds_read_b128 v[92:95], v123 offset:41728
	v_pk_fma_f32 v[106:107], v[70:71], v[46:47], v[106:107] op_sel:[0,1,0]
	v_swap_b32 v61, v62
	v_pk_fma_f32 v[108:109], v[70:71], v[58:59], v[108:109] op_sel:[0,1,0]
	v_pk_mul_f32 v[110:111], v[64:65], v[40:41] op_sel_hi:[1,0]
	v_add_f32_dpp v106, v106, v106 quad_perm:[1,0,3,2] row_mask:0xf bank_mask:0xf bound_ctrl:1
	v_add_f32_dpp v107, v107, v107 quad_perm:[1,0,3,2] row_mask:0xf bank_mask:0xf bound_ctrl:1
	v_pk_fma_f32 v[108:109], v[62:63], v[176:177], v[108:109]
	v_pk_mul_f32 v[112:113], v[66:67], v[40:41] op_sel:[0,1]
	v_add_f32_dpp v106, v106, v106 quad_perm:[2,3,0,1] row_mask:0xf bank_mask:0xf bound_ctrl:1
	v_add_f32_dpp v107, v107, v107 quad_perm:[2,3,0,1] row_mask:0xf bank_mask:0xf bound_ctrl:1
	v_add_f32_dpp v148, v108, v108 row_half_mirror row_mask:0xf bank_mask:0xf bound_ctrl:1
	v_add_f32_dpp v148, v109, v109 row_half_mirror row_mask:0xf bank_mask:0xa
	v_add_f32_dpp v106, v106, v106 row_half_mirror row_mask:0xf bank_mask:0xf bound_ctrl:1
	v_add_f32_dpp v107, v107, v107 row_half_mirror row_mask:0xf bank_mask:0xf bound_ctrl:1
	v_pk_mul_f32 v[144:145], v[68:69], v[42:43] op_sel_hi:[1,0]
	v_pk_mul_f32 v[146:147], v[70:71], v[42:43] op_sel:[0,1]
	v_add_f32_dpp v106, v106, v106 row_mirror row_mask:0xf bank_mask:0xf bound_ctrl:1
	v_add_f32_dpp v107, v107, v107 row_mirror row_mask:0xf bank_mask:0xf bound_ctrl:1
	v_pk_fma_f32 v[110:111], v[60:61], v[52:53], v[110:111] op_sel_hi:[1,0,1]
	v_pk_fma_f32 v[112:113], v[60:61], v[52:53], v[112:113] op_sel:[0,1,0]
	v_pk_fma_f32 v[144:145], v[60:61], v[54:55], v[144:145] op_sel_hi:[1,0,1]
	v_pk_fma_f32 v[146:147], v[60:61], v[54:55], v[146:147] op_sel:[0,1,0]
	v_pk_fma_f32 v[64:65], v[106:107], v[48:49], v[110:111] op_sel_hi:[1,0,1]
	v_pk_fma_f32 v[66:67], v[106:107], v[48:49], v[112:113] op_sel:[0,1,0]
	v_pk_fma_f32 v[68:69], v[106:107], v[50:51], v[144:145] op_sel_hi:[1,0,1]
	v_pk_fma_f32 v[70:71], v[106:107], v[50:51], v[146:147] op_sel:[0,1,0]
	s_waitcnt lgkmcnt(0)
	v_pk_mul_f32 v[106:107], v[64:65], v[76:77] op_sel_hi:[1,0]
	ds_read_b128 v[40:43], v175 offset:5120
	v_pk_mul_f32 v[108:109], v[64:65], v[88:89] op_sel_hi:[1,0]
	ds_read_b128 v[44:47], v175 offset:5136
	v_pk_fma_f32 v[106:107], v[66:67], v[76:77], v[106:107] op_sel:[0,1,0]
	ds_read_b128 v[48:51], v175 offset:5152
	v_pk_fma_f32 v[108:109], v[66:67], v[88:89], v[108:109] op_sel:[0,1,0]
	ds_read_b128 v[52:55], v175 offset:5168
	v_pk_fma_f32 v[106:107], v[68:69], v[78:79], v[106:107] op_sel_hi:[1,0,1]
	ds_read_b128 v[56:59], v175 offset:5184
	v_pk_fma_f32 v[108:109], v[68:69], v[90:91], v[108:109] op_sel_hi:[1,0,1]
	ds_read_b128 v[60:63], v123 offset:41984
	v_pk_fma_f32 v[106:107], v[70:71], v[78:79], v[106:107] op_sel:[0,1,0]
	v_swap_b32 v93, v94
	v_pk_fma_f32 v[108:109], v[70:71], v[90:91], v[108:109] op_sel:[0,1,0]
	v_pk_mul_f32 v[110:111], v[64:65], v[72:73] op_sel_hi:[1,0]
	v_add_f32_dpp v106, v106, v106 quad_perm:[1,0,3,2] row_mask:0xf bank_mask:0xf bound_ctrl:1
	v_add_f32_dpp v107, v107, v107 quad_perm:[1,0,3,2] row_mask:0xf bank_mask:0xf bound_ctrl:1
	v_pk_fma_f32 v[108:109], v[94:95], v[176:177], v[108:109]
	v_pk_mul_f32 v[112:113], v[66:67], v[72:73] op_sel:[0,1]
	v_add_f32_dpp v106, v106, v106 quad_perm:[2,3,0,1] row_mask:0xf bank_mask:0xf bound_ctrl:1
	v_add_f32_dpp v107, v107, v107 quad_perm:[2,3,0,1] row_mask:0xf bank_mask:0xf bound_ctrl:1
	v_add_f32_dpp v149, v108, v108 row_half_mirror row_mask:0xf bank_mask:0xf bound_ctrl:1
	v_add_f32_dpp v149, v109, v109 row_half_mirror row_mask:0xf bank_mask:0xa
	v_add_f32_dpp v106, v106, v106 row_half_mirror row_mask:0xf bank_mask:0xf bound_ctrl:1
	v_add_f32_dpp v107, v107, v107 row_half_mirror row_mask:0xf bank_mask:0xf bound_ctrl:1
	v_pk_mul_f32 v[144:145], v[68:69], v[74:75] op_sel_hi:[1,0]
	v_pk_mul_f32 v[146:147], v[70:71], v[74:75] op_sel:[0,1]
	v_add_f32_dpp v150, v148, v148 row_ror:8 row_mask:0xf bank_mask:0xf bound_ctrl:1
	v_add_f32_dpp v150, v149, v149 row_ror:8 row_mask:0xf bank_mask:0xc
	v_add_f32_dpp v106, v106, v106 row_mirror row_mask:0xf bank_mask:0xf bound_ctrl:1
	v_add_f32_dpp v107, v107, v107 row_mirror row_mask:0xf bank_mask:0xf bound_ctrl:1
	v_pk_fma_f32 v[110:111], v[92:93], v[84:85], v[110:111] op_sel_hi:[1,0,1]
	v_pk_fma_f32 v[112:113], v[92:93], v[84:85], v[112:113] op_sel:[0,1,0]
	v_pk_fma_f32 v[144:145], v[92:93], v[86:87], v[144:145] op_sel_hi:[1,0,1]
	v_pk_fma_f32 v[146:147], v[92:93], v[86:87], v[146:147] op_sel:[0,1,0]
	v_add_f32_dpp v150, v150, v150 quad_perm:[1,0,3,2] row_mask:0xf bank_mask:0xf bound_ctrl:1
	v_pk_fma_f32 v[64:65], v[106:107], v[80:81], v[110:111] op_sel_hi:[1,0,1]
	v_pk_fma_f32 v[66:67], v[106:107], v[80:81], v[112:113] op_sel:[0,1,0]
	v_add_f32_dpp v150, v150, v150 quad_perm:[2,3,0,1] row_mask:0xf bank_mask:0xf bound_ctrl:1
	v_pk_fma_f32 v[68:69], v[106:107], v[82:83], v[144:145] op_sel_hi:[1,0,1]
	v_pk_fma_f32 v[70:71], v[106:107], v[82:83], v[146:147] op_sel:[0,1,0]
	s_mov_b64 exec, s[34:35]
	ds_write_b32 v178, v150 offset:256
	s_mov_b64 exec, -1
	v_add_u32_e32 v175, 0x1400, v175
	v_add_u32_e32 v123, 0x400, v123
	v_add_u32_e32 v178, 0x200, v178
	s_add_i32 s38, s38, -1
	s_cmp_lg_u32 s38, 0
	s_cbranch_scc1 .Lscan_steps
	s_setprio 0
